# v33 + FoX main loop: three of eight bias-table LDS reads hoisted to the top of BOTH half-trips into free VGPRs
# baseline (speedup 1.0000x reference)
.LBB0_790:
	ds_read_b128 v[236:239], v196 offset:256
	ds_read_b128 v[240:243], v196 offset:288
	ds_read_b128 v[244:247], v196 offset:320
	s_add_i32 s0, s1, 0x2000
	s_cmpk_lg_i32 s1, 0x4000
	s_cselect_b32 s71, s0, 0
	v_add_u32_e32 v198, s36, v229
	ds_read_b64_tr_b16 v[160:161], v198 offset:24576
	ds_read_b64_tr_b16 v[162:163], v198 offset:25088
	v_add_f32_e32 v80, v64, v65
	v_add_f32_e32 v80, v66, v80
	v_add_f32_e32 v80, v67, v80
	v_add_f32_e32 v80, v68, v80
	v_add_f32_e32 v100, v69, v80
	v_mfma_f32_32x32x16_bf16 v[80:95], v[96:99], v[128:131], v[32:47]
	v_cvt_pk_bf16_f32 v140, v64, v65
	v_cvt_pk_bf16_f32 v141, v66, v67
	ds_read_b64_tr_b16 v[156:157], v198 offset:28672
	ds_read_b64_tr_b16 v[158:159], v198 offset:29184
	v_add_f32_e32 v64, v70, v100
	v_add_f32_e32 v64, v71, v64
	v_add_f32_e32 v64, v72, v64
	v_add_f32_e32 v64, v73, v64
	v_cvt_pk_bf16_f32 v142, v68, v69
	v_cvt_pk_bf16_f32 v143, v70, v71
	v_mfma_f32_32x32x16_bf16 v[96:111], v[180:183], v[128:131], v[32:47]
	ds_read_b64_tr_b16 v[152:153], v198 offset:25600
	ds_read_b64_tr_b16 v[154:155], v198 offset:26112
	v_mfma_f32_32x32x16_bf16 v[80:95], v[184:187], v[120:123], v[80:95]
	v_add_f32_e32 v64, v74, v64
	v_add_f32_e32 v64, v75, v64
	v_add_f32_e32 v64, v76, v64
	v_add_f32_e32 v64, v77, v64
	v_cvt_pk_bf16_f32 v136, v72, v73
	v_cvt_pk_bf16_f32 v137, v74, v75
	ds_read_b64_tr_b16 v[148:149], v198 offset:29696
	ds_read_b64_tr_b16 v[150:151], v198 offset:30208
	v_add_f32_e32 v64, v78, v64
	v_add_f32_e32 v64, v79, v64
	v_add_f32_e32 v64, v48, v64
	v_add_f32_e32 v64, v49, v64
	v_cvt_pk_bf16_f32 v138, v76, v77
	v_cvt_pk_bf16_f32 v139, v78, v79
	v_mfma_f32_32x32x16_bf16 v[96:111], v[144:147], v[120:123], v[96:111]
	ds_read_b64_tr_b16 v[144:145], v198 offset:26624
	ds_read_b64_tr_b16 v[146:147], v198 offset:27136
	v_mfma_f32_32x32x16_bf16 v[80:95], v[176:179], v[116:119], v[80:95]
	v_add_f32_e32 v64, v50, v64
	v_add_f32_e32 v64, v51, v64
	v_add_f32_e32 v64, v52, v64
	v_add_f32_e32 v64, v53, v64
	v_cvt_pk_bf16_f32 v132, v48, v49
	v_cvt_pk_bf16_f32 v133, v50, v51
	ds_read_b64_tr_b16 v[184:185], v198 offset:30720
	ds_read_b64_tr_b16 v[186:187], v198 offset:31232
	v_add_f32_e32 v48, v54, v64
	v_add_f32_e32 v48, v55, v48
	v_add_f32_e32 v48, v56, v48
	v_add_f32_e32 v48, v57, v48
	v_cvt_pk_bf16_f32 v134, v52, v53
	v_cvt_pk_bf16_f32 v135, v54, v55
	v_mfma_f32_32x32x16_bf16 v[96:111], v[168:171], v[116:119], v[96:111]
	ds_read_b64_tr_b16 v[180:181], v198 offset:27648
	ds_read_b64_tr_b16 v[182:183], v198 offset:28160
	v_mfma_f32_32x32x16_bf16 v[80:95], v[172:175], v[112:115], v[80:95]
	v_add_f32_e32 v48, v58, v48
	v_add_f32_e32 v48, v59, v48
	v_add_f32_e32 v48, v60, v48
	v_add_f32_e32 v48, v61, v48
	v_cvt_pk_bf16_f32 v124, v56, v57
	v_cvt_pk_bf16_f32 v125, v58, v59
	ds_read_b64_tr_b16 v[176:177], v198 offset:31744
	ds_read_b64_tr_b16 v[178:179], v198 offset:32256
	v_add_f32_e32 v48, v62, v48
	v_add_f32_e32 v48, v63, v48
	v_add_f32_e32 v168, 0, v48
	v_cvt_pk_bf16_f32 v126, v60, v61
	v_cvt_pk_bf16_f32 v127, v62, v63
	v_mfma_f32_32x32x16_bf16 v[96:111], v[164:167], v[112:115], v[96:111]
	s_waitcnt lgkmcnt(8)
	ds_read_b128 v[76:79], v196 offset:352
	ds_read_b128 v[48:51], v196 offset:384
	ds_read_b128 v[52:55], v196 offset:416
	ds_read_b128 v[56:59], v196 offset:448
	ds_read_b128 v[60:63], v196 offset:480
	s_add_i32 s0, s1, s65
	s_mov_b32 m0, s0
	s_nop 0
	global_load_lds_dwordx4 v[194:195], off
	s_add_i32 s0, s71, s68
	s_mov_b32 m0, s0
	s_nop 0
	global_load_lds_dwordx4 v[192:193], off
	s_waitcnt lgkmcnt(4)
	v_add_f32_e32 v64, v80, v236
	v_add_f32_e32 v65, v81, v237
	v_add_f32_e32 v66, v82, v238
	v_add_f32_e32 v67, v83, v239
	v_add_f32_e32 v68, v84, v240
	v_add_f32_e32 v69, v85, v241
	v_add_f32_e32 v70, v86, v242
	v_add_f32_e32 v71, v87, v243
	v_add_f32_e32 v72, v88, v244
	v_add_f32_e32 v73, v89, v245
	v_add_f32_e32 v74, v90, v246
	v_add_f32_e32 v75, v91, v247
	v_add_f32_e32 v76, v92, v76
	v_add_f32_e32 v77, v93, v77
	v_add_f32_e32 v78, v94, v78
	v_add_f32_e32 v79, v95, v79
	s_waitcnt lgkmcnt(1)
	v_add_f32_e32 v48, v96, v48
	v_add_f32_e32 v49, v97, v49
	v_add_f32_e32 v50, v98, v50
	v_add_f32_e32 v51, v99, v51
	v_add_f32_e32 v52, v100, v52
	v_add_f32_e32 v53, v101, v53
	v_add_f32_e32 v54, v102, v54
	v_add_f32_e32 v55, v103, v55
	v_add_f32_e32 v56, v104, v56
	v_add_f32_e32 v57, v105, v57
	v_add_f32_e32 v58, v106, v58
	v_add_f32_e32 v59, v107, v59
	s_waitcnt lgkmcnt(0)
	v_add_f32_e32 v60, v108, v60
	v_add_f32_e32 v61, v109, v61
	v_add_f32_e32 v62, v110, v62
	v_add_f32_e32 v63, v111, v63
	v_max_f32_e32 v80, v64, v65
	v_max3_f32 v81, v66, v67, v49
	v_max3_f32 v80, v80, v48, v50
	v_max3_f32 v80, v80, v51, v68
	v_max3_f32 v81, v81, v70, v71
	v_max3_f32 v80, v80, v69, v52
	v_max3_f32 v81, v81, v54, v55
	v_max3_f32 v80, v80, v53, v72
	v_max3_f32 v81, v81, v74, v75
	v_max3_f32 v80, v80, v73, v56
	v_max3_f32 v81, v81, v58, v59
	v_max3_f32 v80, v80, v57, v76
	v_max3_f32 v81, v81, v78, v79
	v_max3_f32 v80, v80, v77, v60
	v_max3_f32 v81, v81, v62, v63
	v_max3_f32 v80, v80, v61, v81
	v_mov_b32_e32 v81, v80
	s_nop 1
	v_permlane32_swap_b32_e32 v80, v81
	v_max_f32_e32 v81, v81, v81
	v_max_f32_e32 v80, v80, v80
	v_max_f32_e32 v80, v80, v81
	v_cmp_lt_f32_e32 vcc, s61, v80
	s_cmp_lg_u64 vcc, 0
	v_add_f32_e32 v231, v197, v168
	s_cselect_b64 s[10:11], -1, 0
	s_cbranch_vccnz .LBB0_798
